# GEMM phase prologues: K-tile 1 staging loads issued before the first wait (one exposed round trip instead of two per phase start); XCC rank discovery poll loads batched
# baseline (speedup 1.0000x reference)
; #define PG8_STAGE(bufoff, gbase, voff) do { _Pragma("unroll") for (int _i = 0; _i < 2; ++_i) \
;         __builtin_amdgcn_global_load_lds((const unsigned*)((const char*)(gbase) + (voff)[_i]), (PG8_LAS unsigned*)(lds + (bufoff) + ldsw + _i * 8192), 16, 0, 0); } while (0)
; #define PG8_WAIT_V(n) asm volatile("s_waitcnt vmcnt(" #n ")" ::: "memory")
; #define PG8_BAR __builtin_amdgcn_s_barrier()
; template <class Epi, class Sched, bool ALIGN_EPI = false, bool SP2 = false>
; __device__ __forceinline__ void gemm_phase(PG8_LAS unsigned char* lds, const Gemm g, const Sched& S, const Epi& E) {
;     ...
;     } else {
;         PG8_STAGE(PG8_SB(0, 0), cB, voffB); PG8_STAGE(PG8_SA(0, 0), cA, voffA); PG8_STAGE(PG8_SB(0, 1), cB + hstepB, voffB); PG8_STAGE(PG8_SA(0, 1), cA + hstepA, voffA);
;         if (wr == 1) PG8_BAR;
;         PG8_WAIT_V(4); PG8_BAR;
;         PG8_STAGE(PG8_SB(1, 0), cB + kstep, voffB); PG8_STAGE(PG8_SA(1, 0), cA + kstep, voffA); PG8_STAGE(PG8_SB(1, 1), cB + hstepB + kstep, voffB);
;         PG8_WAIT_V(6); PG8_BAR;
;     }
.LBB0_24:
	s_sext_i32_i16 s63, s6
	s_add_u32 s6, s92, 0x8000000
	s_addc_u32 s7, s93, 0
	s_add_u32 s8, s92, 0x3e6c0000
	v_readlane_b32 s14, v255, 33
	s_addc_u32 s9, s93, 0
	s_mul_hi_u32 s13, s14, 0x58000
	s_mul_i32 s14, s14, 0x58000
	s_add_u32 s14, s92, s14
	s_addc_u32 s13, s93, s13
	s_add_u32 s53, s14, 0x3eb00000
	s_addc_u32 s54, s13, 0
	s_lshl_b32 s11, s11, 5
	v_and_b32_e32 v17, 48, v16
	v_lshlrev_b32_e32 v18, 6, v16
	s_movk_i32 s13, 0x3c0
	v_lshlrev_b32_e32 v16, 2, v16
	s_and_b32 s56, s11, 0x60
	s_add_i32 m0, s49, 0x18000
	v_lshl_add_u64 v[8:9], v[8:9], 0, s[22:23]
	s_lshl_b32 s55, s12, 6
	s_lshl_b32 s12, s12, 13
	v_and_or_b32 v17, v18, s13, v17
	v_and_b32_e32 v16, 32, v16
	s_lshl_b32 s11, s56, 7
	global_load_lds_dwordx4 v[8:9], off
	v_lshl_add_u64 v[6:7], v[6:7], 0, s[22:23]
	s_add_i32 m0, s49, 0x1a000
	s_add_i32 s57, s49, 0x8000
	s_add_i32 s58, s49, 0xa000
	v_bitop3_b32 v18, v17, s12, v16 bitop3:0xde
	global_load_lds_dwordx4 v[6:7], off
	v_lshl_add_u64 v[2:3], v[2:3], 0, s[22:23]
	s_mov_b32 m0, s57
	s_add_u32 s12, s42, 0x40080
	global_load_lds_dwordx4 v[2:3], off
	v_lshl_add_u64 v[2:3], v[4:5], 0, s[22:23]
	s_mov_b32 m0, s58
	s_addc_u32 s13, s43, 0
	global_load_lds_dwordx4 v[2:3], off
	s_add_i32 m0, s49, 0x1c000
	v_lshl_add_u64 v[2:3], s[12:13], 0, v[0:1]
	global_load_lds_dwordx4 v[2:3], off
	v_lshl_add_u64 v[2:3], s[12:13], 0, v[146:147]
	s_add_i32 m0, s49, 0x1e000
	s_cmpk_lt_u32 s10, 0x100
	global_load_lds_dwordx4 v[2:3], off
	s_waitcnt vmcnt(8)
	s_barrier
	v_lshlrev_b32_e32 v2, 14, v14
	v_and_b32_e32 v2, 0xffff8000, v2
	v_lshl_add_u32 v2, v13, 11, v2
	v_and_b32_e32 v3, 1, v14
	v_lshl_or_b32 v2, v3, 6, v2
	v_lshl_add_u32 v152, v15, 1, v2
	v_lshlrev_b32_e32 v2, 14, v10
	v_and_b32_e32 v2, 0xffff8000, v2
	s_waitcnt vmcnt(6)
	v_lshl_add_u32 v2, v11, 11, v2
	v_and_b32_e32 v3, 1, v10
	v_readlane_b32 s12, v255, 28
	v_lshl_or_b32 v2, v3, 6, v2
	v_bitop3_b32 v165, s11, v17, v16 bitop3:0xf6
	s_cselect_b64 s[10:11], -1, 0
	s_ashr_i32 s59, s55, 31
	s_ashr_i32 s60, s12, 31
	v_mov_b32_e32 v153, v1
	v_lshl_add_u32 v154, v12, 1, v2
	v_mov_b32_e32 v155, v1
	s_mov_b32 s61, 0
	v_add_u32_e32 v166, 0, v18
	s_lshl_b32 s62, s56, 2
	v_readlane_b32 s15, v255, 34
	s_barrier
	s_branch .LBB0_27

; #define PG8_STAGE(bufoff, gbase, voff) do { _Pragma("unroll") for (int _i = 0; _i < 2; ++_i) \
;         __builtin_amdgcn_global_load_lds((const unsigned*)((const char*)(gbase) + (voff)[_i]), (PG8_LAS unsigned*)(lds + (bufoff) + ldsw + _i * 8192), 16, 0, 0); } while (0)
; #define PG8_WAIT_V(n) asm volatile("s_waitcnt vmcnt(" #n ")" ::: "memory")
; #define PG8_BAR __builtin_amdgcn_s_barrier()
; template <class Epi, class Sched, bool ALIGN_EPI = false, bool SP2 = false>
; __device__ __forceinline__ void gemm_phase(PG8_LAS unsigned char* lds, const Gemm g, const Sched& S, const Epi& E) {
;     ...
;     } else {
;         PG8_STAGE(PG8_SB(0, 0), cB, voffB); PG8_STAGE(PG8_SA(0, 0), cA, voffA); PG8_STAGE(PG8_SB(0, 1), cB + hstepB, voffB); PG8_STAGE(PG8_SA(0, 1), cA + hstepA, voffA);
;         if (wr == 1) PG8_BAR;
;         PG8_WAIT_V(4); PG8_BAR;
;         PG8_STAGE(PG8_SB(1, 0), cB + kstep, voffB); PG8_STAGE(PG8_SA(1, 0), cA + kstep, voffA); PG8_STAGE(PG8_SB(1, 1), cB + hstepB + kstep, voffB);
;         PG8_WAIT_V(6); PG8_BAR;
;     }
.LBB0_50:
	v_readlane_b32 s10, v255, 35
	v_readlane_b32 s11, v255, 36
	s_lshl_b64 s[10:11], s[10:11], 2
	s_add_u32 s19, s92, s10
	s_addc_u32 s34, s93, s11
	s_add_u32 s61, s19, 0x3dc02000
	s_addc_u32 s62, s34, 0
	s_add_u32 s10, s92, 0x28000000
	v_readlane_b32 s14, v255, 33
	s_addc_u32 s11, s93, 0
	v_readlane_b32 s15, v255, 34
	s_lshl_b32 s30, s14, 10
	s_lshl_b64 s[14:15], s[30:31], 2
	s_waitcnt lgkmcnt(0)
	s_add_u32 s12, s12, s14
	s_addc_u32 s13, s13, s15
	s_add_u32 s30, s19, 0x3dc04000
	s_addc_u32 s63, s34, 0
	s_add_u32 s14, s92, 0x3e6c0000
	s_addc_u32 s15, s93, 0
	s_lshl_b32 s17, s17, 5
	v_and_b32_e32 v16, 48, v12
	v_lshlrev_b32_e32 v17, 6, v12
	s_movk_i32 s19, 0x3c0
	v_lshlrev_b32_e32 v12, 2, v12
	s_and_b32 s65, s17, 0x60
	s_add_i32 m0, s57, 0x18000
	v_lshl_add_u64 v[8:9], v[8:9], 0, s[22:23]
	s_lshl_b32 s64, s18, 6
	s_lshl_b32 s18, s18, 13
	v_and_or_b32 v16, v17, s19, v16
	v_and_b32_e32 v12, 32, v12
	s_lshl_b32 s17, s65, 7
	global_load_lds_dwordx4 v[8:9], off
	v_lshl_add_u64 v[6:7], v[6:7], 0, s[22:23]
	s_add_i32 m0, s57, 0x1a000
	s_add_i32 s66, s57, 0x8000
	s_add_i32 s67, s57, 0xa000
	v_bitop3_b32 v17, v16, s18, v12 bitop3:0xde
	global_load_lds_dwordx4 v[6:7], off
	v_lshl_add_u64 v[2:3], v[2:3], 0, s[22:23]
	s_mov_b32 m0, s66
	s_add_u32 s18, s46, 0x40080
	global_load_lds_dwordx4 v[2:3], off
	v_lshl_add_u64 v[2:3], v[4:5], 0, s[22:23]
	s_mov_b32 m0, s67
	s_addc_u32 s19, s47, 0
	global_load_lds_dwordx4 v[2:3], off
	s_add_i32 m0, s57, 0x1c000
	v_lshl_add_u64 v[2:3], s[18:19], 0, v[148:149]
	global_load_lds_dwordx4 v[2:3], off
	v_lshl_add_u64 v[2:3], s[18:19], 0, v[150:151]
	s_add_i32 m0, s57, 0x1e000
	s_cmpk_lt_u32 s16, 0x100
	global_load_lds_dwordx4 v[2:3], off
	s_waitcnt vmcnt(8)
	s_barrier
	v_lshlrev_b32_e32 v2, 14, v13
	v_and_b32_e32 v2, 0xffff8000, v2
	v_lshl_add_u32 v2, v14, 11, v2
	v_and_b32_e32 v3, 1, v13
	v_lshl_or_b32 v2, v3, 6, v2
	v_lshl_add_u32 v152, v15, 1, v2
	v_lshlrev_b32_e32 v2, 14, v0
	v_readlane_b32 s18, v255, 28
	v_and_b32_e32 v2, 0xffff8000, v2
	v_bitop3_b32 v182, s17, v16, v12 bitop3:0xf6
	s_waitcnt vmcnt(6)
	s_cselect_b64 s[16:17], -1, 0
	s_ashr_i32 s68, s64, 31
	s_ashr_i32 s69, s18, 31
	s_ashr_i32 s72, s4, 31
	v_lshl_add_u32 v2, v10, 11, v2
	v_and_b32_e32 v0, 1, v0
	s_cmp_lg_u64 s[92:93], 0
	v_lshl_or_b32 v0, v0, 6, v2
	s_cselect_b64 s[18:19], -1, 0
	v_mov_b32_e32 v153, v1
	v_lshl_add_u32 v154, v11, 1, v0
	v_mov_b32_e32 v155, v1
	s_mov_b32 s73, 0
	v_add_u32_e32 v183, 0, v17
	s_barrier
	s_branch .LBB0_53

; #define PG8_STAGE(bufoff, gbase, voff) do { _Pragma("unroll") for (int _i = 0; _i < 2; ++_i) \
;         __builtin_amdgcn_global_load_lds((const unsigned*)((const char*)(gbase) + (voff)[_i]), (PG8_LAS unsigned*)(lds + (bufoff) + ldsw + _i * 8192), 16, 0, 0); } while (0)
; #define PG8_WAIT_V(n) asm volatile("s_waitcnt vmcnt(" #n ")" ::: "memory")
; #define PG8_BAR __builtin_amdgcn_s_barrier()
; template <class Epi, class Sched, bool ALIGN_EPI = false, bool SP2 = false>
; __device__ __forceinline__ void gemm_phase(PG8_LAS unsigned char* lds, const Gemm g, const Sched& S, const Epi& E) {
;     ...
;     } else {
;         PG8_STAGE(PG8_SB(0, 0), cB, voffB); PG8_STAGE(PG8_SA(0, 0), cA, voffA); PG8_STAGE(PG8_SB(0, 1), cB + hstepB, voffB); PG8_STAGE(PG8_SA(0, 1), cA + hstepA, voffA);
;         if (wr == 1) PG8_BAR;
;         PG8_WAIT_V(4); PG8_BAR;
;         PG8_STAGE(PG8_SB(1, 0), cB + kstep, voffB); PG8_STAGE(PG8_SA(1, 0), cA + kstep, voffA); PG8_STAGE(PG8_SB(1, 1), cB + hstepB + kstep, voffB);
;         PG8_WAIT_V(6); PG8_BAR;
;     }
.LBB0_202:
	s_add_u32 s12, s92, 0x18000000
	s_sext_i32_i8 s9, s2
	s_addc_u32 s13, s93, 0
	s_lshl_b32 s56, s3, 6
	v_and_b32_e32 v17, 48, v16
	s_lshl_b32 s2, s3, 13
	v_lshlrev_b32_e32 v18, 6, v16
	s_movk_i32 s3, 0x3c0
	v_lshlrev_b32_e32 v16, 2, v16
	v_and_or_b32 v17, v18, s3, v17
	v_and_b32_e32 v16, 32, v16
	v_bitop3_b32 v18, v17, s2, v16 bitop3:0xde
	s_lshl_b32 s2, s14, 5
	s_and_b32 s57, s2, 0x60
	s_add_i32 m0, s52, 0x18000
	v_lshl_add_u64 v[8:9], v[8:9], 0, s[22:23]
	s_lshl_b32 s2, s57, 7
	global_load_lds_dwordx4 v[8:9], off
	v_lshl_add_u64 v[6:7], v[6:7], 0, s[22:23]
	s_add_i32 m0, s52, 0x1a000
	s_add_i32 s58, s52, 0x8000
	s_add_i32 s59, s52, 0xa000
	v_bitop3_b32 v152, s2, v17, v16 bitop3:0xf6
	global_load_lds_dwordx4 v[6:7], off
	v_lshl_add_u64 v[2:3], v[2:3], 0, s[22:23]
	s_mov_b32 m0, s58
	s_add_u32 s2, s6, 0x40080
	global_load_lds_dwordx4 v[2:3], off
	v_lshl_add_u64 v[2:3], v[4:5], 0, s[22:23]
	s_mov_b32 m0, s59
	s_addc_u32 s3, s7, 0
	global_load_lds_dwordx4 v[2:3], off
	s_add_i32 m0, s52, 0x1c000
	v_lshl_add_u64 v[2:3], s[2:3], 0, v[0:1]
	global_load_lds_dwordx4 v[2:3], off
	v_lshl_add_u64 v[2:3], s[2:3], 0, v[142:143]
	s_add_i32 m0, s52, 0x1e000
	s_ashr_i32 s60, s56, 31
	global_load_lds_dwordx4 v[2:3], off
	s_waitcnt vmcnt(8)
	s_barrier
	v_lshlrev_b32_e32 v2, 14, v10
	v_and_b32_e32 v2, 0xffff8000, v2
	v_lshl_add_u32 v2, v11, 11, v2
	v_and_b32_e32 v3, 1, v10
	v_lshl_or_b32 v2, v3, 6, v2
	v_lshl_add_u32 v144, v12, 1, v2
	v_lshlrev_b32_e32 v2, 14, v13
	v_and_b32_e32 v2, 0xffff8000, v2
	s_waitcnt vmcnt(6)
	v_lshl_add_u32 v2, v14, 11, v2
	v_and_b32_e32 v3, 1, v13
	s_cmpk_lt_u32 s8, 0x100
	v_readlane_b32 s2, v255, 28
	v_lshl_or_b32 v2, v3, 6, v2
	s_cselect_b64 s[14:15], -1, 0
	s_ashr_i32 s61, s2, 31
	v_mov_b32_e32 v145, v1
	v_lshl_add_u32 v146, v15, 1, v2
	v_mov_b32_e32 v147, v1
	s_mov_b32 s62, 0
	v_add_u32_e32 v153, 0, v18
	s_barrier
	s_branch .LBB0_205

; #define PG8_STAGE(bufoff, gbase, voff) do { _Pragma("unroll") for (int _i = 0; _i < 2; ++_i) \
;         __builtin_amdgcn_global_load_lds((const unsigned*)((const char*)(gbase) + (voff)[_i]), (PG8_LAS unsigned*)(lds + (bufoff) + ldsw + _i * 8192), 16, 0, 0); } while (0)
; #define PG8_WAIT_V(n) asm volatile("s_waitcnt vmcnt(" #n ")" ::: "memory")
; #define PG8_BAR __builtin_amdgcn_s_barrier()
; template <class Epi, class Sched, bool ALIGN_EPI = false, bool SP2 = false>
; __device__ __forceinline__ void gemm_phase(PG8_LAS unsigned char* lds, const Gemm g, const Sched& S, const Epi& E) {
;     ...
;     } else {
;         PG8_STAGE(PG8_SB(0, 0), cB, voffB); PG8_STAGE(PG8_SA(0, 0), cA, voffA); PG8_STAGE(PG8_SB(0, 1), cB + hstepB, voffB); PG8_STAGE(PG8_SA(0, 1), cA + hstepA, voffA);
;         if (wr == 1) PG8_BAR;
;         PG8_WAIT_V(4); PG8_BAR;
;         PG8_STAGE(PG8_SB(1, 0), cB + kstep, voffB); PG8_STAGE(PG8_SA(1, 0), cA + kstep, voffA); PG8_STAGE(PG8_SB(1, 1), cB + hstepB + kstep, voffB);
;         PG8_WAIT_V(6); PG8_BAR;
;     }
.LBB0_480:
	v_readlane_b32 s12, v255, 33
	v_readlane_b32 s13, v255, 34
	s_mul_i32 s30, s12, 0x60
	s_lshl_b64 s[12:13], s[30:31], 2
	s_waitcnt lgkmcnt(0)
	s_add_u32 s8, s8, s12
	s_addc_u32 s9, s9, s13
	s_and_b32 s3, s10, 3
	s_lshl_b32 s72, s11, 6
	v_and_b32_e32 v10, 48, v0
	s_lshl_b32 s10, s11, 13
	v_lshlrev_b32_e32 v11, 6, v0
	s_movk_i32 s11, 0x3c0
	v_lshlrev_b32_e32 v0, 2, v0
	v_and_or_b32 v10, v11, s11, v10
	v_and_b32_e32 v0, 32, v0
	s_add_i32 m0, s61, 0x18000
	v_lshl_add_u64 v[8:9], v[8:9], 0, s[22:23]
	v_bitop3_b32 v11, v10, s10, v0 bitop3:0xde
	s_lshl_b32 s73, s3, 5
	s_lshl_b32 s10, s3, 12
	global_load_lds_dwordx4 v[8:9], off
	v_lshl_add_u64 v[6:7], v[6:7], 0, s[22:23]
	s_add_i32 m0, s61, 0x1a000
	s_add_i32 s86, s61, 0x8000
	s_add_i32 s87, s61, 0xa000
	v_bitop3_b32 v153, v10, s10, v0 bitop3:0xde
	global_load_lds_dwordx4 v[6:7], off
	v_lshl_add_u64 v[2:3], v[2:3], 0, s[22:23]
	s_mov_b32 m0, s86
	s_add_u32 s10, s38, 0x10080
	global_load_lds_dwordx4 v[2:3], off
	v_lshl_add_u64 v[2:3], v[4:5], 0, s[22:23]
	s_mov_b32 m0, s87
	s_addc_u32 s11, s39, 0
	global_load_lds_dwordx4 v[2:3], off
	s_add_i32 m0, s61, 0x1c000
	v_lshl_add_u64 v[2:3], s[10:11], 0, v[136:137]
	global_load_lds_dwordx4 v[2:3], off
	v_lshl_add_u64 v[2:3], s[10:11], 0, v[140:141]
	s_add_i32 m0, s61, 0x1e000
	s_cmpk_lt_u32 s40, 0x100
	global_load_lds_dwordx4 v[2:3], off
	s_waitcnt vmcnt(8)
	s_barrier
	s_cselect_b64 s[10:11], -1, 0
	s_add_u32 s12, s92, 0x30000000
	s_addc_u32 s13, s93, 0
	s_add_u32 s14, s92, 0x3de00000
	s_addc_u32 s15, s93, 0
	s_add_u32 s16, s92, 0x3e640000
	s_addc_u32 s17, s93, 0
	s_add_u32 s18, s92, 0x3e910000
	s_addc_u32 s19, s93, 0
	s_ashr_i32 s88, s72, 31
	s_add_u32 s44, s92, 0x36000000
	s_addc_u32 s45, s93, 0
	s_bfe_u32 s30, s40, 0x10006
	s_or_b32 s89, s30, -6
	s_cmp_lt_u32 s3, 2
	s_cselect_b64 s[46:47], -1, 0
	s_add_u32 s48, s92, 0x3e600000
	v_readlane_b32 s30, v255, 28
	s_waitcnt vmcnt(6)
	s_addc_u32 s49, s93, 0
	s_ashr_i32 s94, s30, 31
	s_ashr_i32 s3, s37, 31
	s_add_u32 s50, s30, s37
	s_addc_u32 s51, s94, s3
	v_add_u32_e32 v159, 0, v11
	s_barrier
	s_branch .LBB0_484

; #define PG8_STAGE(bufoff, gbase, voff) do { _Pragma("unroll") for (int _i = 0; _i < 2; ++_i) \
;         __builtin_amdgcn_global_load_lds((const unsigned*)((const char*)(gbase) + (voff)[_i]), (PG8_LAS unsigned*)(lds + (bufoff) + ldsw + _i * 8192), 16, 0, 0); } while (0)
; #define PG8_WAIT_V(n) asm volatile("s_waitcnt vmcnt(" #n ")" ::: "memory")
; #define PG8_BAR __builtin_amdgcn_s_barrier()
; template <class Epi, class Sched, bool ALIGN_EPI = false, bool SP2 = false>
; __device__ __forceinline__ void gemm_phase(PG8_LAS unsigned char* lds, const Gemm g, const Sched& S, const Epi& E) {
;     ...
;     } else {
;         PG8_STAGE(PG8_SB(0, 0), cB, voffB); PG8_STAGE(PG8_SA(0, 0), cA, voffA); PG8_STAGE(PG8_SB(0, 1), cB + hstepB, voffB); PG8_STAGE(PG8_SA(0, 1), cA + hstepA, voffA);
;         if (wr == 1) PG8_BAR;
;         PG8_WAIT_V(4); PG8_BAR;
;         PG8_STAGE(PG8_SB(1, 0), cB + kstep, voffB); PG8_STAGE(PG8_SA(1, 0), cA + kstep, voffA); PG8_STAGE(PG8_SB(1, 1), cB + hstepB + kstep, voffB);
;         PG8_WAIT_V(6); PG8_BAR;
;     }
.LBB0_542:
	s_add_u32 s10, s92, 0x8000000
	s_addc_u32 s11, s93, 0
	s_add_u32 s3, s92, 0xc000000
	v_writelane_b32 v255, s3, 45
	s_addc_u32 s3, s93, 0
	s_add_u32 s12, s92, 0x18000000
	v_writelane_b32 v255, s3, 46
	s_addc_u32 s13, s93, 0
	v_writelane_b32 v255, s12, 47
	s_add_u32 s96, s92, 0x3e600000
	s_addc_u32 s97, s93, 0
	v_writelane_b32 v255, s13, 48
	s_add_u32 s14, s92, 0x3e910000
	v_readlane_b32 s12, v255, 33
	s_addc_u32 s15, s93, 0
	s_lshl_b32 s30, s12, 6
	v_readlane_b32 s13, v255, 34
	s_add_u32 s16, s92, 0x3e680000
	s_addc_u32 s17, s93, 0
	s_lshl_b64 s[12:13], s[12:13], 18
	s_add_u32 s3, s92, s12
	s_addc_u32 s13, s93, s13
	s_add_u32 s12, s3, 0x3ea00000
	s_addc_u32 s13, s13, 0
	s_and_b32 s38, s9, 3
	s_add_i32 m0, s86, 0x18000
	v_lshl_add_u64 v[8:9], v[8:9], 0, s[22:23]
	s_lshl_b32 s49, s18, 6
	s_lshl_b32 s3, s18, 13
	s_lshl_b32 s50, s38, 5
	s_lshl_b32 s37, s38, 12
	global_load_lds_dwordx4 v[8:9], off
	v_lshl_add_u64 v[6:7], v[6:7], 0, s[22:23]
	s_add_i32 m0, s86, 0x1a000
	s_add_i32 s51, s86, 0x8000
	s_add_i32 s94, s86, 0xa000
	global_load_lds_dwordx4 v[6:7], off
	v_lshl_add_u64 v[2:3], v[2:3], 0, s[22:23]
	s_mov_b32 m0, s51
	s_add_u32 s18, s6, 0x40080
	global_load_lds_dwordx4 v[2:3], off
	v_lshl_add_u64 v[2:3], v[4:5], 0, s[22:23]
	s_mov_b32 m0, s94
	s_addc_u32 s19, s7, 0
	global_load_lds_dwordx4 v[2:3], off
	s_add_i32 m0, s86, 0x1c000
	v_lshl_add_u64 v[2:3], s[18:19], 0, v[148:149]
	global_load_lds_dwordx4 v[2:3], off
	v_lshl_add_u64 v[2:3], s[18:19], 0, v[152:153]
	s_add_i32 m0, s86, 0x1e000
	s_movk_i32 s18, 0x3c0
	global_load_lds_dwordx4 v[2:3], off
	s_waitcnt vmcnt(8)
	s_barrier
	v_and_b32_e32 v2, 48, v0
	v_lshlrev_b32_e32 v3, 6, v0
	v_lshlrev_b32_e32 v0, 2, v0
	v_and_or_b32 v2, v3, s18, v2
	v_and_b32_e32 v0, 32, v0
	v_bitop3_b32 v3, v2, s3, v0 bitop3:0xde
	v_bitop3_b32 v161, v2, s37, v0 bitop3:0xde
	s_cmpk_lt_u32 s8, 0x100
	v_lshlrev_b32_e32 v0, 14, v13
	s_cselect_b64 s[18:19], -1, 0
	s_bfe_u32 s3, s9, 0x10001
	v_and_b32_e32 v0, 0xffff8000, v0
	s_orn2_b32 s3, s3, 23
	v_lshl_add_u32 v0, v14, 11, v0
	v_and_b32_e32 v2, 1, v13
	v_writelane_b32 v255, s3, 49
	v_lshl_or_b32 v0, v2, 6, v0
	s_ashr_i32 s95, s49, 31
	s_and_b32 s3, s50, 32
	v_writelane_b32 v255, s38, 50
	v_lshl_add_u32 v154, v15, 1, v0
	v_lshlrev_b32_e32 v0, 14, v10
	s_cmp_eq_u32 s38, 0
	v_readlane_b32 s8, v255, 28
	v_and_b32_e32 v0, 0xffff8000, v0
	s_waitcnt vmcnt(6)
	s_cselect_b64 s[82:83], -1, 0
	s_ashr_i32 s8, s8, 31
	s_ashr_i32 s9, s4, 31
	v_lshl_add_u32 v0, v11, 11, v0
	v_and_b32_e32 v2, 1, v10
	s_add_u32 s84, s92, 0x14000000
	v_lshl_or_b32 v0, v2, 6, v0
	s_mov_b32 s48, 0
	s_addc_u32 s85, s93, 0
	v_mov_b32_e32 v155, v1
	v_lshl_add_u32 v156, v12, 1, v0
	v_mov_b32_e32 v157, v1
	v_add_u32_e32 v163, 0, v3
	s_lshl_b32 s56, s3, 1
	s_lshl_b64 s[58:59], s[30:31], 2
	s_barrier
	s_branch .LBB0_545

; #define PG8_STAGE(bufoff, gbase, voff) do { _Pragma("unroll") for (int _i = 0; _i < 2; ++_i) \
;         __builtin_amdgcn_global_load_lds((const unsigned*)((const char*)(gbase) + (voff)[_i]), (PG8_LAS unsigned*)(lds + (bufoff) + ldsw + _i * 8192), 16, 0, 0); } while (0)
; #define PG8_WAIT_V(n) asm volatile("s_waitcnt vmcnt(" #n ")" ::: "memory")
; #define PG8_BAR __builtin_amdgcn_s_barrier()
; template <class Epi, class Sched, bool ALIGN_EPI = false, bool SP2 = false>
; __device__ __forceinline__ void gemm_phase(PG8_LAS unsigned char* lds, const Gemm g, const Sched& S, const Epi& E) {
;     ...
;     } else {
;         PG8_STAGE(PG8_SB(0, 0), cB, voffB); PG8_STAGE(PG8_SA(0, 0), cA, voffA); PG8_STAGE(PG8_SB(0, 1), cB + hstepB, voffB); PG8_STAGE(PG8_SA(0, 1), cA + hstepA, voffA);
;         if (wr == 1) PG8_BAR;
;         PG8_WAIT_V(4); PG8_BAR;
;         PG8_STAGE(PG8_SB(1, 0), cB + kstep, voffB); PG8_STAGE(PG8_SA(1, 0), cA + kstep, voffA); PG8_STAGE(PG8_SB(1, 1), cB + hstepB + kstep, voffB);
;         PG8_WAIT_V(6); PG8_BAR;
;     }
.LBB0_677:
	v_readlane_b32 s4, v255, 33
	s_add_i32 s15, s4, 1
	s_cmp_gt_u32 s4, 2
	s_cselect_b64 s[16:17], -1, 0
	s_cmp_lt_u32 s4, 3
	v_readlane_b32 s44, v255, 35
	v_readlane_b32 s5, v255, 34
	s_cselect_b64 s[12:13], -1, 0
	s_add_u32 s41, s92, 0x3dc00000
	v_readlane_b32 s45, v255, 36
	s_addc_u32 s42, s93, 0
	s_lshl_b64 s[4:5], s[44:45], 2
	s_add_u32 s4, s41, s4
	s_addc_u32 s5, s42, s5
	s_add_u32 s57, s4, 0x5000
	s_mul_hi_u32 s40, s15, 0x18000
	s_addc_u32 s58, s5, 0
	s_lshl_b32 s15, s15, 10
	s_and_b64 s[4:5], s[16:17], exec
	s_cselect_b32 s30, 0, s15
	s_lshl_b64 s[4:5], s[30:31], 2
	s_waitcnt lgkmcnt(0)
	s_add_u32 s4, s8, s4
	s_addc_u32 s5, s9, s5
	s_add_i32 s15, s44, 0x18400
	s_and_b64 s[8:9], s[16:17], exec
	s_cselect_b32 s9, 0, s40
	s_cselect_b32 s8, 0, s15
	s_lshl_b64 s[8:9], s[8:9], 2
	s_add_u32 s30, s41, s8
	s_addc_u32 s60, s42, s9
	s_add_u32 s8, s92, 0x3e680000
	s_addc_u32 s9, s93, 0
	s_lshl_b32 s11, s11, 5
	v_and_b32_e32 v18, 48, v12
	v_lshlrev_b32_e32 v19, 6, v12
	s_movk_i32 s15, 0x3c0
	v_lshlrev_b32_e32 v12, 2, v12
	s_and_b32 s62, s11, 0x60
	s_add_i32 m0, s53, 0x18000
	v_lshl_add_u64 v[8:9], v[8:9], 0, s[22:23]
	s_lshl_b32 s61, s14, 6
	s_lshl_b32 s14, s14, 13
	v_and_or_b32 v18, v19, s15, v18
	v_and_b32_e32 v12, 32, v12
	s_lshl_b32 s11, s62, 7
	global_load_lds_dwordx4 v[8:9], off
	v_lshl_add_u64 v[6:7], v[6:7], 0, s[22:23]
	s_add_i32 m0, s53, 0x1a000
	s_add_i32 s63, s53, 0x8000
	s_add_i32 s64, s53, 0xa000
	v_bitop3_b32 v19, v18, s14, v12 bitop3:0xde
	global_load_lds_dwordx4 v[6:7], off
	v_lshl_add_u64 v[2:3], v[2:3], 0, s[22:23]
	s_mov_b32 m0, s63
	s_add_u32 s14, s38, 0xb0080
	global_load_lds_dwordx4 v[2:3], off
	v_lshl_add_u64 v[2:3], v[4:5], 0, s[22:23]
	s_mov_b32 m0, s64
	s_addc_u32 s15, s39, 0
	global_load_lds_dwordx4 v[2:3], off
	s_add_i32 m0, s53, 0x1c000
	v_lshl_add_u64 v[2:3], s[14:15], 0, v[148:149]
	global_load_lds_dwordx4 v[2:3], off
	v_lshl_add_u64 v[2:3], s[14:15], 0, v[150:151]
	s_add_i32 m0, s53, 0x1e000
	s_cmpk_lt_u32 s10, 0x100
	global_load_lds_dwordx4 v[2:3], off
	s_waitcnt vmcnt(8)
	s_barrier
	v_readlane_b32 s14, v255, 28
	v_bitop3_b32 v180, s11, v18, v12 bitop3:0xf6
	s_cselect_b64 s[10:11], -1, 0
	s_ashr_i32 s65, s61, 31
	s_ashr_i32 s66, s14, 31
	s_ashr_i32 s67, s37, 31
	s_cmp_lg_u64 s[92:93], 0
	s_movk_i32 s16, 0xb00
	s_cselect_b64 s[14:15], -1, 0
	v_lshrrev_b32_e32 v2, 1, v0
	v_mul_lo_u32 v0, v11, s16
	s_mov_b32 s17, 0xb000
	s_and_b64 s[12:13], s[12:13], s[14:15]
	v_mad_u64_u32 v[2:3], s[14:15], v2, s17, v[0:1]
	v_or_b32_e32 v0, v2, v10
	v_add_lshl_u32 v0, v0, v13, 1
	s_mov_b64 s[40:41], 0xb0080
	v_lshl_add_u64 v[152:153], v[0:1], 0, s[40:41]
	v_lshrrev_b32_e32 v2, 1, v14
	v_mul_lo_u32 v0, v16, s16
	v_mad_u64_u32 v[2:3], s[14:15], v2, s17, v[0:1]
	s_waitcnt vmcnt(6)
	v_or_b32_e32 v0, v2, v15
	v_add_lshl_u32 v0, v0, v17, 1
	s_mov_b32 s59, 0
	v_lshl_add_u64 v[154:155], v[0:1], 0, s[40:41]
	v_add_u32_e32 v181, 0, v19
	s_barrier
	s_branch .LBB0_680

; __device__ __forceinline__ unsigned xb_ld(unsigned* p)              { return __hip_atomic_load(p, __ATOMIC_RELAXED, __HIP_MEMORY_SCOPE_AGENT); }
; __device__ __forceinline__ void xcd_barrier_complete(unsigned* bar, unsigned x, unsigned& nloc, unsigned& nx) {
;     const unsigned G = gridDim.x * gridDim.y * gridDim.z;
;     unsigned sum, cnt, mine, sp = 0u;
;     for (;;) {
;         sum = 0u; cnt = 0u; mine = 0u;
; #pragma unroll
;         for (unsigned j = 0; j < 16; ++j) { const unsigned c = xb_ld(&bar[XB_XCNT(j)]); sum += c; cnt += (c > 0u) ? 1u : 0u; mine = (j == x) ? c : mine; }
;         if (sum == G) break;
;         __builtin_amdgcn_s_sleep(1);
;         if ((++sp & 255u) == 0u) { if (xb_ld(&bar[XB_TMO])) break; if (sp > XB_SPIN_CAP) { atomicAdd(&bar[XB_TMO], 1u); break; } }
;     }
;     nloc = mine > 0u ? mine : 1u; nx = cnt > 0u ? cnt : 1u;
.LBB0_960:
	v_readlane_b32 s4, v254, 13
	v_readlane_b32 s5, v254, 14
	v_readlane_b32 s6, v255, 21
	s_nop 3
	global_load_dword v0, v1, s[4:5] sc1
	v_readlane_b32 s4, v254, 15
	v_readlane_b32 s5, v254, 16
	s_waitcnt lgkmcnt(0)
	s_nop 3
	global_load_dword v2, v1, s[4:5] sc1
	v_readlane_b32 s4, v254, 17
	v_readlane_b32 s5, v254, 18
	s_nop 0
	s_nop 0
	s_nop 2
	global_load_dword v3, v1, s[4:5] sc1
	v_readlane_b32 s4, v254, 19
	v_readlane_b32 s5, v254, 20
	s_nop 0
	s_nop 0
	s_nop 2
	global_load_dword v4, v1, s[4:5] sc1
	v_readlane_b32 s4, v254, 21
	v_readlane_b32 s5, v254, 22
	s_nop 0
	s_nop 0
	s_nop 2
	global_load_dword v5, v1, s[4:5] sc1
	v_readlane_b32 s4, v254, 23
	v_readlane_b32 s5, v254, 24
	s_nop 0
	s_nop 0
	s_nop 2
	global_load_dword v6, v1, s[4:5] sc1
	v_readlane_b32 s4, v254, 25
	v_readlane_b32 s5, v254, 26
	s_nop 0
	s_nop 0
	s_nop 2
	global_load_dword v7, v1, s[4:5] sc1
	v_readlane_b32 s4, v254, 27
	v_readlane_b32 s5, v254, 28
	s_nop 0
	s_nop 0
	s_nop 2
	global_load_dword v8, v1, s[4:5] sc1
	v_readlane_b32 s4, v254, 29
	v_readlane_b32 s5, v254, 30
	s_nop 0
	s_nop 0
	s_nop 2
	global_load_dword v9, v1, s[4:5] sc1
	v_readlane_b32 s4, v254, 31
	v_readlane_b32 s5, v254, 32
	s_nop 0
	s_nop 0
	s_nop 2
	global_load_dword v10, v1, s[4:5] sc1
	v_readlane_b32 s4, v254, 33
	v_readlane_b32 s5, v254, 34
	s_nop 0
	s_nop 0
	s_nop 2
	global_load_dword v11, v1, s[4:5] sc1
	v_readlane_b32 s4, v254, 35
	v_readlane_b32 s5, v254, 36
	s_nop 0
	s_nop 0
	s_nop 2
	global_load_dword v12, v1, s[4:5] sc1
	v_readlane_b32 s4, v254, 37
	v_readlane_b32 s5, v254, 38
	s_nop 0
	s_nop 0
	s_nop 2
	global_load_dword v13, v1, s[4:5] sc1
	v_readlane_b32 s4, v254, 39
	v_readlane_b32 s5, v254, 40
	s_nop 0
	s_nop 0
	s_nop 2
	global_load_dword v14, v1, s[4:5] sc1
	v_readlane_b32 s4, v254, 41
	v_readlane_b32 s5, v254, 42
	s_nop 0
	s_nop 0
	s_nop 2
	global_load_dword v15, v1, s[4:5] sc1
	v_readlane_b32 s4, v254, 43
	v_readlane_b32 s5, v254, 44
	s_nop 0
	s_nop 0
	s_nop 2
	global_load_dword v16, v1, s[4:5] sc1
	s_mov_b64 s[4:5], -1
	s_nop 0
	s_nop 0
	s_waitcnt vmcnt(0)
	v_add_u32_e32 v17, v2, v0
	v_add_u32_e32 v17, v17, v3
	v_add_u32_e32 v17, v17, v4
	v_add_u32_e32 v17, v17, v5
	v_add_u32_e32 v17, v17, v6
	v_add_u32_e32 v17, v17, v7
	v_add_u32_e32 v17, v17, v8
	v_add_u32_e32 v17, v17, v9
	v_add_u32_e32 v17, v17, v10
	v_add_u32_e32 v17, v17, v11
	v_add_u32_e32 v17, v17, v12
	v_add_u32_e32 v17, v17, v13
	v_add_u32_e32 v17, v17, v14
	v_add_u32_e32 v17, v17, v15
	v_add_u32_e32 v17, v17, v16
	v_cmp_eq_u32_e32 vcc, s6, v17
	s_mov_b64 s[6:7], -1
	s_cbranch_vccnz .LBB0_959
	s_and_b32 s4, s10, 0xff
	s_cmp_eq_u32 s4, 0
	s_mov_b64 s[4:5], -1
	s_mov_b64 s[8:9], -1
	s_sleep 1
	s_cbranch_scc1 .LBB0_964
	s_and_b64 vcc, exec, s[8:9]
	s_cbranch_vccz .LBB0_959
